# S1 partial-sum: 32 loads in flight at once (were 4 dependent batches)
# speedup vs baseline: 1.0058x; 1.0058x over previous
; __global__ void __launch_bounds__(512, 2) mega(Params p_unused) {
;     ...
;       for (int i = bid * 512 + threadIdx.x; i < 5 * 12288; i += G * 512) { const int n = i % 12288; float s = p.b_ada[n];
; #pragma unroll 8
;           for (int k = 0; k < 32; ++k) s += modp[(size_t)k * (2 * 5 * 12288) + i];
;           MOD[i] = s; } }
.LBB0_93:
	s_mov_b32 s13, 0
	s_mov_b32 s12, 0x12580000
	v_lshl_add_u64 v[8:9], v[0:1], 0, s[12:13]
	global_load_dword v204, v[8:9], off
	s_mov_b32 s12, 0x125f8000
	v_lshl_add_u64 v[8:9], v[0:1], 0, s[12:13]
	global_load_dword v205, v[8:9], off
	s_mov_b32 s12, 0x12670000
	v_lshl_add_u64 v[8:9], v[0:1], 0, s[12:13]
	global_load_dword v206, v[8:9], off
	s_mov_b32 s12, 0x126e8000
	v_lshl_add_u64 v[8:9], v[0:1], 0, s[12:13]
	global_load_dword v207, v[8:9], off
	s_mov_b32 s12, 0x12760000
	v_lshl_add_u64 v[8:9], v[0:1], 0, s[12:13]
	global_load_dword v208, v[8:9], off
	s_mov_b32 s12, 0x127d8000
	v_lshl_add_u64 v[8:9], v[0:1], 0, s[12:13]
	global_load_dword v209, v[8:9], off
	s_mov_b32 s12, 0x12850000
	v_lshl_add_u64 v[8:9], v[0:1], 0, s[12:13]
	global_load_dword v210, v[8:9], off
	s_mov_b32 s12, 0x128c8000
	v_lshl_add_u64 v[8:9], v[0:1], 0, s[12:13]
	global_load_dword v211, v[8:9], off
	s_mov_b32 s12, 0x12940000
	v_lshl_add_u64 v[8:9], v[0:1], 0, s[12:13]
	global_load_dword v212, v[8:9], off
	s_mov_b32 s12, 0x129b8000
	v_lshl_add_u64 v[8:9], v[0:1], 0, s[12:13]
	global_load_dword v213, v[8:9], off
	s_mov_b32 s12, 0x12a30000
	v_lshl_add_u64 v[8:9], v[0:1], 0, s[12:13]
	global_load_dword v214, v[8:9], off
	s_mov_b32 s12, 0x12aa8000
	v_lshl_add_u64 v[8:9], v[0:1], 0, s[12:13]
	global_load_dword v215, v[8:9], off
	s_mov_b32 s12, 0x12b20000
	v_lshl_add_u64 v[8:9], v[0:1], 0, s[12:13]
	global_load_dword v216, v[8:9], off
	s_mov_b32 s12, 0x12b98000
	v_lshl_add_u64 v[8:9], v[0:1], 0, s[12:13]
	global_load_dword v217, v[8:9], off
	s_mov_b32 s12, 0x12c10000
	v_lshl_add_u64 v[8:9], v[0:1], 0, s[12:13]
	global_load_dword v218, v[8:9], off
	s_mov_b32 s12, 0x12c88000
	v_lshl_add_u64 v[8:9], v[0:1], 0, s[12:13]
	global_load_dword v219, v[8:9], off
	s_mov_b32 s12, 0x12d00000
	v_lshl_add_u64 v[8:9], v[0:1], 0, s[12:13]
	global_load_dword v220, v[8:9], off
	s_mov_b32 s12, 0x12d78000
	v_lshl_add_u64 v[8:9], v[0:1], 0, s[12:13]
	global_load_dword v221, v[8:9], off
	s_mov_b32 s12, 0x12df0000
	v_lshl_add_u64 v[8:9], v[0:1], 0, s[12:13]
	global_load_dword v222, v[8:9], off
	s_mov_b32 s12, 0x12e68000
	v_lshl_add_u64 v[8:9], v[0:1], 0, s[12:13]
	global_load_dword v223, v[8:9], off
	s_mov_b32 s12, 0x12ee0000
	v_lshl_add_u64 v[8:9], v[0:1], 0, s[12:13]
	global_load_dword v224, v[8:9], off
	s_mov_b32 s12, 0x12f58000
	v_lshl_add_u64 v[8:9], v[0:1], 0, s[12:13]
	global_load_dword v225, v[8:9], off
	s_mov_b32 s12, 0x12fd0000
	v_lshl_add_u64 v[8:9], v[0:1], 0, s[12:13]
	global_load_dword v226, v[8:9], off
	s_mov_b32 s12, 0x13048000
	v_lshl_add_u64 v[8:9], v[0:1], 0, s[12:13]
	global_load_dword v227, v[8:9], off
	s_mov_b32 s12, 0x130c0000
	v_lshl_add_u64 v[8:9], v[0:1], 0, s[12:13]
	global_load_dword v228, v[8:9], off
	s_mov_b32 s12, 0x13138000
	v_lshl_add_u64 v[8:9], v[0:1], 0, s[12:13]
	global_load_dword v229, v[8:9], off
	s_mov_b32 s12, 0x131b0000
	v_lshl_add_u64 v[8:9], v[0:1], 0, s[12:13]
	global_load_dword v230, v[8:9], off
	s_mov_b32 s12, 0x13228000
	v_lshl_add_u64 v[8:9], v[0:1], 0, s[12:13]
	global_load_dword v231, v[8:9], off
	s_mov_b32 s12, 0x132a0000
	v_lshl_add_u64 v[8:9], v[0:1], 0, s[12:13]
	global_load_dword v232, v[8:9], off
	s_mov_b32 s12, 0x13318000
	v_lshl_add_u64 v[8:9], v[0:1], 0, s[12:13]
	global_load_dword v233, v[8:9], off
	s_mov_b32 s12, 0x13390000
	v_lshl_add_u64 v[8:9], v[0:1], 0, s[12:13]
	global_load_dword v234, v[8:9], off
	s_mov_b32 s12, 0x13408000
	v_lshl_add_u64 v[8:9], v[0:1], 0, s[12:13]
	global_load_dword v235, v[8:9], off
	s_waitcnt vmcnt(31)
	v_add_f32_e32 v3, v4, v204
	s_waitcnt vmcnt(30)
	v_add_f32_e32 v3, v3, v205
	s_waitcnt vmcnt(29)
	v_add_f32_e32 v3, v3, v206
	s_waitcnt vmcnt(28)
	v_add_f32_e32 v3, v3, v207
	s_waitcnt vmcnt(27)
	v_add_f32_e32 v3, v3, v208
	s_waitcnt vmcnt(26)
	v_add_f32_e32 v3, v3, v209
	s_waitcnt vmcnt(25)
	v_add_f32_e32 v3, v3, v210
	s_waitcnt vmcnt(24)
	v_add_f32_e32 v3, v3, v211
	s_waitcnt vmcnt(23)
	v_add_f32_e32 v3, v3, v212
	s_waitcnt vmcnt(22)
	v_add_f32_e32 v3, v3, v213
	s_waitcnt vmcnt(21)
	v_add_f32_e32 v3, v3, v214
	s_waitcnt vmcnt(20)
	v_add_f32_e32 v3, v3, v215
	s_waitcnt vmcnt(19)
	v_add_f32_e32 v3, v3, v216
	s_waitcnt vmcnt(18)
	v_add_f32_e32 v3, v3, v217
	s_waitcnt vmcnt(17)
	v_add_f32_e32 v3, v3, v218
	s_waitcnt vmcnt(16)
	v_add_f32_e32 v3, v3, v219
	s_waitcnt vmcnt(15)
	v_add_f32_e32 v3, v3, v220
	s_waitcnt vmcnt(14)
	v_add_f32_e32 v3, v3, v221
	s_waitcnt vmcnt(13)
	v_add_f32_e32 v3, v3, v222
	s_waitcnt vmcnt(12)
	v_add_f32_e32 v3, v3, v223
	s_waitcnt vmcnt(11)
	v_add_f32_e32 v3, v3, v224
	s_waitcnt vmcnt(10)
	v_add_f32_e32 v3, v3, v225
	s_waitcnt vmcnt(9)
	v_add_f32_e32 v3, v3, v226
	s_waitcnt vmcnt(8)
	v_add_f32_e32 v3, v3, v227
	s_waitcnt vmcnt(7)
	v_add_f32_e32 v3, v3, v228
	s_waitcnt vmcnt(6)
	v_add_f32_e32 v3, v3, v229
	s_waitcnt vmcnt(5)
	v_add_f32_e32 v3, v3, v230
	s_waitcnt vmcnt(4)
	v_add_f32_e32 v3, v3, v231
	s_waitcnt vmcnt(3)
	v_add_f32_e32 v3, v3, v232
	s_waitcnt vmcnt(2)
	v_add_f32_e32 v3, v3, v233
	s_waitcnt vmcnt(1)
	v_add_f32_e32 v3, v3, v234
	s_waitcnt vmcnt(0)
	v_add_f32_e32 v4, v3, v235
	v_ashrrev_i32_e32 v3, 31, v2
	v_lshl_add_u64 v[6:7], v[2:3], 2, s[8:9]
	v_add_u32_e32 v2, s50, v2
	v_cmp_lt_i32_e32 vcc, s14, v2
	s_or_b64 s[6:7], vcc, s[6:7]
	v_lshl_add_u64 v[0:1], v[0:1], 0, s[10:11]
	global_store_dword v[6:7], v4, off
	s_andn2_b64 exec, exec, s[6:7]
	s_cbranch_execnz .LBB0_92
